# prep lora-up loop re-emitted with 12 loads in flight and counted waits; readout gate-weight loads batched
# speedup vs baseline: 1.1041x; 1.0092x over previous
; __device__ __forceinline__ float sigmoidf_(float x) { return 1.0f / (1.0f + __expf(-x)); }
; __device__ __forceinline__ void phase_prep(const Params& p, int l, float* smem) {
;     ...
;       const f16* wbase = lwt + (size_t)m * RD * 64;
;       const float* bias = (kind == 0 ? p.in[I_DW0] : p.in[I_A0]) + ((size_t)l * 2 + z) * RD;
;       f16* dst = (kind == 0 ? dE : dA) + ((size_t)z * NTOK + row) * RD;
; #pragma unroll 4
;       for (int nb = 0; nb < 24; ++nb) {
;         const f16* wp = wbase + (size_t)(nb * 16 + lq) * 64 + g * 16;
;         f16x8 w0 = *(const f16x8*)wp, w1 = *(const f16x8*)(wp + 8);
;         f32x4 a = f32x4{0.f, 0.f, 0.f, 0.f};
;         a = __builtin_amdgcn_mfma_f32_16x16x32_f16(w0, xf[0], a, 0, 0, 0);
;         a = __builtin_amdgcn_mfma_f32_16x16x32_f16(w1, xf[1], a, 0, 0, 0);
;         const int c = nb * 16 + 4 * g;
;         float4 b4 = *(const float4*)(bias + c);
;         const float ba[4] = {b4.x, b4.y, b4.z, b4.w};
;         f16x4 o4;
; #pragma unroll
;         for (int i = 0; i < 4; ++i) {
;           float xv = ba[i] + a[i];
;           if (kind == 0) {
;             o4[i] = (f16)(0.60653065971f * sigmoidf_(xv));
;           } else {
;             o4[i] = (f16)sigmoidf_(xv);
;           }
;         }
;         *(f16x4*)(dst + c) = o4;
;       }
.LBB0_761:
	v_lshl_add_u64 v[18:19], v[28:29], 0, v[12:13]
	v_add_co_u32_e32 v20, vcc, 0x1eda8000, v18
	s_nop 1
	v_addc_co_u32_e32 v21, vcc, 0, v19, vcc
	v_lshl_add_u64 v[14:15], v[10:11], 0, s[8:9]
	v_add_co_u32_e32 v22, vcc, 0x1eda9000, v18
	s_nop 1
	v_addc_co_u32_e32 v23, vcc, 0, v19, vcc
	global_load_dwordx4 v[64:67], v[20:21], off
	global_load_dwordx4 v[68:71], v[20:21], off offset:16
	global_load_dwordx4 v[96:99], v[14:15], off
	global_load_dwordx4 v[72:75], v[20:21], off offset:2048
	global_load_dwordx4 v[76:79], v[20:21], off offset:2064
	global_load_dwordx4 v[100:103], v[14:15], off offset:64
	global_load_dwordx4 v[80:83], v[22:23], off
	global_load_dwordx4 v[84:87], v[22:23], off offset:16
	global_load_dwordx4 v[104:107], v[14:15], off offset:128
	global_load_dwordx4 v[88:91], v[22:23], off offset:2048
	global_load_dwordx4 v[92:95], v[22:23], off offset:2064
	global_load_dwordx4 v[108:111], v[14:15], off offset:192
	v_lshl_add_u64 v[16:17], v[28:29], 0, v[8:9]
	s_add_u32 s8, s8, 0x100
	s_addc_u32 s9, s9, 0
	s_waitcnt vmcnt(9)
	v_mfma_f32_16x16x32_f16 v[48:51], v[64:67], v[0:3], 0
	v_mfma_f32_16x16x32_f16 v[48:51], v[68:71], v[4:7], v[48:51]
	s_nop 7
	s_nop 1
	v_add_f32_e32 v24, v48, v96
	v_add_f32_e32 v25, v49, v97
	v_add_f32_e32 v26, v50, v98
	v_add_f32_e32 v27, v51, v99
	v_mul_f32_e32 v24, 0xbfb8aa3b, v24
	v_mul_f32_e32 v25, 0xbfb8aa3b, v25
	v_mul_f32_e32 v26, 0xbfb8aa3b, v26
	v_mul_f32_e32 v27, 0xbfb8aa3b, v27
	v_exp_f32_e32 v24, v24
	v_exp_f32_e32 v25, v25
	v_exp_f32_e32 v26, v26
	v_exp_f32_e32 v27, v27
	v_add_f32_e32 v24, 1.0, v24
	v_add_f32_e32 v25, 1.0, v25
	v_add_f32_e32 v26, 1.0, v26
	v_add_f32_e32 v27, 1.0, v27
	v_rcp_f32_e32 v24, v24
	v_rcp_f32_e32 v25, v25
	v_rcp_f32_e32 v26, v26
	v_rcp_f32_e32 v27, v27
	v_mul_f32_e32 v52, 0x3f1b4598, v24
	v_mul_f32_e32 v53, 0x3f1b4598, v25
	v_mul_f32_e32 v54, 0x3f1b4598, v26
	v_mul_f32_e32 v56, 0x3f1b4598, v27
	v_cndmask_b32_e64 v24, v24, v52, s[6:7]
	v_cndmask_b32_e64 v25, v25, v53, s[6:7]
	v_cndmask_b32_e64 v26, v26, v54, s[6:7]
	v_cndmask_b32_e64 v27, v27, v56, s[6:7]
	v_cvt_pk_f16_f32 v52, v24, v25
	v_cvt_pk_f16_f32 v53, v26, v27
	global_store_dwordx2 v[16:17], v[52:53], off
	s_waitcnt vmcnt(7)
	v_mfma_f32_16x16x32_f16 v[48:51], v[72:75], v[0:3], 0
	v_mfma_f32_16x16x32_f16 v[48:51], v[76:79], v[4:7], v[48:51]
	s_nop 7
	s_nop 1
	v_add_f32_e32 v24, v48, v100
	v_add_f32_e32 v25, v49, v101
	v_add_f32_e32 v26, v50, v102
	v_add_f32_e32 v27, v51, v103
	v_mul_f32_e32 v24, 0xbfb8aa3b, v24
	v_mul_f32_e32 v25, 0xbfb8aa3b, v25
	v_mul_f32_e32 v26, 0xbfb8aa3b, v26
	v_mul_f32_e32 v27, 0xbfb8aa3b, v27
	v_exp_f32_e32 v24, v24
	v_exp_f32_e32 v25, v25
	v_exp_f32_e32 v26, v26
	v_exp_f32_e32 v27, v27
	v_add_f32_e32 v24, 1.0, v24
	v_add_f32_e32 v25, 1.0, v25
	v_add_f32_e32 v26, 1.0, v26
	v_add_f32_e32 v27, 1.0, v27
	v_rcp_f32_e32 v24, v24
	v_rcp_f32_e32 v25, v25
	v_rcp_f32_e32 v26, v26
	v_rcp_f32_e32 v27, v27
	v_mul_f32_e32 v52, 0x3f1b4598, v24
	v_mul_f32_e32 v53, 0x3f1b4598, v25
	v_mul_f32_e32 v54, 0x3f1b4598, v26
	v_mul_f32_e32 v56, 0x3f1b4598, v27
	v_cndmask_b32_e64 v24, v24, v52, s[6:7]
	v_cndmask_b32_e64 v25, v25, v53, s[6:7]
	v_cndmask_b32_e64 v26, v26, v54, s[6:7]
	v_cndmask_b32_e64 v27, v27, v56, s[6:7]
	v_cvt_pk_f16_f32 v52, v24, v25
	v_cvt_pk_f16_f32 v53, v26, v27
	global_store_dwordx2 v[16:17], v[52:53], off offset:32
	s_waitcnt vmcnt(5)
	v_mfma_f32_16x16x32_f16 v[48:51], v[80:83], v[0:3], 0
	v_mfma_f32_16x16x32_f16 v[48:51], v[84:87], v[4:7], v[48:51]
	s_nop 7
	s_nop 1
	v_add_f32_e32 v24, v48, v104
	v_add_f32_e32 v25, v49, v105
	v_add_f32_e32 v26, v50, v106
	v_add_f32_e32 v27, v51, v107
	v_mul_f32_e32 v24, 0xbfb8aa3b, v24
	v_mul_f32_e32 v25, 0xbfb8aa3b, v25
	v_mul_f32_e32 v26, 0xbfb8aa3b, v26
	v_mul_f32_e32 v27, 0xbfb8aa3b, v27
	v_exp_f32_e32 v24, v24
	v_exp_f32_e32 v25, v25
	v_exp_f32_e32 v26, v26
	v_exp_f32_e32 v27, v27
	v_add_f32_e32 v24, 1.0, v24
	v_add_f32_e32 v25, 1.0, v25
	v_add_f32_e32 v26, 1.0, v26
	v_add_f32_e32 v27, 1.0, v27
	v_rcp_f32_e32 v24, v24
	v_rcp_f32_e32 v25, v25
	v_rcp_f32_e32 v26, v26
	v_rcp_f32_e32 v27, v27
	v_mul_f32_e32 v52, 0x3f1b4598, v24
	v_mul_f32_e32 v53, 0x3f1b4598, v25
	v_mul_f32_e32 v54, 0x3f1b4598, v26
	v_mul_f32_e32 v56, 0x3f1b4598, v27
	v_cndmask_b32_e64 v24, v24, v52, s[6:7]
	v_cndmask_b32_e64 v25, v25, v53, s[6:7]
	v_cndmask_b32_e64 v26, v26, v54, s[6:7]
	v_cndmask_b32_e64 v27, v27, v56, s[6:7]
	v_cvt_pk_f16_f32 v52, v24, v25
	v_cvt_pk_f16_f32 v53, v26, v27
	global_store_dwordx2 v[16:17], v[52:53], off offset:64
	s_waitcnt vmcnt(3)
	v_mfma_f32_16x16x32_f16 v[48:51], v[88:91], v[0:3], 0
	v_mfma_f32_16x16x32_f16 v[48:51], v[92:95], v[4:7], v[48:51]
	s_nop 7
	s_nop 1
	v_add_f32_e32 v24, v48, v108
	v_add_f32_e32 v25, v49, v109
	v_add_f32_e32 v26, v50, v110
	v_add_f32_e32 v27, v51, v111
	v_mul_f32_e32 v24, 0xbfb8aa3b, v24
	v_mul_f32_e32 v25, 0xbfb8aa3b, v25
	v_mul_f32_e32 v26, 0xbfb8aa3b, v26
	v_mul_f32_e32 v27, 0xbfb8aa3b, v27
	v_exp_f32_e32 v24, v24
	v_exp_f32_e32 v25, v25
	v_exp_f32_e32 v26, v26
	v_exp_f32_e32 v27, v27
	v_add_f32_e32 v24, 1.0, v24
	v_add_f32_e32 v25, 1.0, v25
	v_add_f32_e32 v26, 1.0, v26
	v_add_f32_e32 v27, 1.0, v27
	v_rcp_f32_e32 v24, v24
	v_rcp_f32_e32 v25, v25
	v_rcp_f32_e32 v26, v26
	v_rcp_f32_e32 v27, v27
	v_mul_f32_e32 v52, 0x3f1b4598, v24
	v_mul_f32_e32 v53, 0x3f1b4598, v25
	v_mul_f32_e32 v54, 0x3f1b4598, v26
	v_mul_f32_e32 v56, 0x3f1b4598, v27
	v_cndmask_b32_e64 v24, v24, v52, s[6:7]
	v_cndmask_b32_e64 v25, v25, v53, s[6:7]
	v_cndmask_b32_e64 v26, v26, v54, s[6:7]
	v_cndmask_b32_e64 v27, v27, v56, s[6:7]
	v_cvt_pk_f16_f32 v52, v24, v25
	v_cvt_pk_f16_f32 v53, v26, v27
	global_store_dwordx2 v[16:17], v[52:53], off offset:96
	v_lshl_add_u64 v[8:9], v[8:9], 0, s[84:85]
	s_mov_b64 s[10:11], 0x2000
	v_lshl_add_u64 v[12:13], v[12:13], 0, s[10:11]
	s_cmpk_eq_i32 s8, 0x600
	s_cbranch_scc0 .LBB0_761
	s_add_i32 s16, s16, s17
	s_add_i32 s18, s18, s19
	s_cmpk_gt_i32 s16, 0x207f
	s_cbranch_scc0 .LBB0_715

; __device__ __forceinline__ float sigmoidf_(float x) { return 1.0f / (1.0f + __expf(-x)); }
; __device__ __forceinline__ void phase_readout(const Params& p, int l, float* smem) {
;     ...
;   for (int it = gw; it < (NTOK / 16) * NH; it += nw) {
;     const int hh = it % NH, row = (it / NH) * 16 + lq;
;     f32x4 ga[4];
; #pragma unroll
;     for (int nb = 0; nb < 4; ++nb) ga[nb] = f32x4{0.f, 0.f, 0.f, 0.f};
; #pragma unroll
;     for (int ks = 0; ks < 5; ++ks) {
;       f16x8 xf = *(const f16x8*)(dGD + (size_t)row * 160 + ks * 32 + g * 8);
; #pragma unroll
;       for (int e = 0; e < 8; ++e) xf[e] = (f16)sigmoidf_((float)xf[e]);
; #pragma unroll
;       for (int nb = 0; nb < 4; ++nb) {
;         f16x8 wf = *(const f16x8*)(gwt + (size_t)(hh * HD + nb * 16 + lq) * 160 + ks * 32 + g * 8);
;         ga[nb] = __builtin_amdgcn_mfma_f32_16x16x32_f16(wf, xf, ga[nb], 0, 0, 0);
;       }
;     }
.LBB0_1056:
	s_mul_hi_i32 s8, s5, 0x2aaaaaab
	s_lshr_b32 s9, s8, 31
	s_add_i32 s10, s8, s9
	v_lshl_or_b32 v16, s10, 4, v45
	v_mad_i64_i32 v[18:19], s[8:9], v16, s49, v[40:41]
	global_load_dwordx4 v[0:3], v[18:19], off
	s_mul_i32 s8, s10, 0xfffffe80
	s_mul_i32 s10, s10, 0xffff1000
	v_add_u32_e32 v4, s10, v107
	v_ashrrev_i32_e32 v5, 31, v4
	v_lshl_add_u64 v[20:21], v[4:5], 1, v[42:43]
	s_movk_i32 s9, 0x1000
	s_add_i32 s8, s6, s8
	v_add_u32_e32 v100, s8, v44
	v_ashrrev_i32_e32 v101, 31, v100
	v_ashrrev_i32_e32 v17, 31, v16
	s_add_i32 s5, s5, s28
	s_add_i32 s6, s6, s7
	s_waitcnt vmcnt(0)
	v_cvt_f32_f16_e32 v6, v0
	v_cvt_f32_f16_sdwa v0, v0 dst_sel:DWORD dst_unused:UNUSED_PAD src0_sel:WORD_1
	v_mul_f32_e32 v6, 0xbfb8aa3b, v6
	v_exp_f32_e32 v6, v6
	v_mul_f32_e32 v0, 0xbfb8aa3b, v0
	v_add_f32_e32 v6, 1.0, v6
	s_nop 0
	v_rcp_f32_e32 v8, v6
	s_nop 0
	v_mul_f32_e32 v7, 1.0, v8
	v_mov_b32_e32 v6, v7
	v_cvt_f16_f32_e32 v8, v6
	v_exp_f32_e32 v6, v0
	v_cvt_f32_f16_e32 v0, v1
	v_mul_f32_e32 v0, 0xbfb8aa3b, v0
	v_exp_f32_e32 v7, v0
	s_nop 0
	v_pk_add_f32 v[6:7], v[6:7], 1.0 op_sel_hi:[1,0]
	s_nop 0
	s_nop 0
	v_rcp_f32_e32 v9, v7
	s_nop 0
	v_mul_f32_e32 v0, 1.0, v9
	s_nop 0
	v_rcp_f32_e32 v9, v6
	s_nop 0
	v_mul_f32_e32 v7, 1.0, v9
	v_mov_b32_e32 v6, v7
	v_cvt_pk_f16_f32 v6, v6, v0
	v_cvt_f32_f16_sdwa v0, v1 dst_sel:DWORD dst_unused:UNUSED_PAD src0_sel:WORD_1
	v_cvt_f32_f16_e32 v1, v2
	v_pack_b32_f16 v12, v8, v6
	v_mul_f32_e32 v0, 0xbfb8aa3b, v0
	v_mul_f32_e32 v1, 0xbfb8aa3b, v1
	v_exp_f32_e32 v0, v0
	v_exp_f32_e32 v1, v1
	s_nop 0
	v_pk_add_f32 v[0:1], v[0:1], 1.0 op_sel_hi:[1,0]
	s_nop 0
	s_nop 0
	v_rcp_f32_e32 v8, v1
	s_nop 0
	v_mul_f32_e32 v7, 1.0, v8
	v_mov_b32_e32 v1, v7
	s_nop 0
	v_rcp_f32_e32 v8, v0
	s_nop 0
	v_mul_f32_e32 v7, 1.0, v8
	v_mov_b32_e32 v0, v7
	v_cvt_pk_f16_f32 v7, v0, v1
	v_cvt_f32_f16_sdwa v0, v2 dst_sel:DWORD dst_unused:UNUSED_PAD src0_sel:WORD_1
	v_cvt_f32_f16_e32 v1, v3
	v_alignbit_b32 v13, v7, v6, 16
	v_mul_f32_e32 v0, 0xbfb8aa3b, v0
	v_mul_f32_e32 v1, 0xbfb8aa3b, v1
	v_exp_f32_e32 v0, v0
	v_exp_f32_e32 v1, v1
	s_nop 0
	v_pk_add_f32 v[0:1], v[0:1], 1.0 op_sel_hi:[1,0]
	s_nop 0
	s_nop 0
	v_rcp_f32_e32 v6, v1
	s_nop 0
	v_mul_f32_e32 v2, 1.0, v6
	v_mov_b32_e32 v1, v2
	s_nop 0
	v_rcp_f32_e32 v6, v0
	s_nop 0
	v_mul_f32_e32 v2, 1.0, v6
	v_mov_b32_e32 v0, v2
	v_cvt_pk_f16_f32 v0, v0, v1
	v_cvt_f32_f16_sdwa v1, v3 dst_sel:DWORD dst_unused:UNUSED_PAD src0_sel:WORD_1
	v_alignbit_b32 v14, v0, v7, 16
	v_mul_f32_e32 v1, 0xbfb8aa3b, v1
	v_exp_f32_e32 v1, v1
	s_nop 0
	v_add_f32_e32 v1, 1.0, v1
	s_nop 0
	v_rcp_f32_e32 v3, v1
	s_nop 0
	v_mul_f32_e32 v2, 1.0, v3
	v_add_co_u32_e32 v22, vcc, s9, v20
	v_mov_b32_e32 v1, v2
	s_nop 0
	v_addc_co_u32_e32 v23, vcc, 0, v21, vcc
	s_movk_i32 s9, 0x2000
	v_cvt_f16_f32_e32 v1, v1
	v_add_co_u32_e32 v54, vcc, s9, v20
	s_movk_i32 s9, 0x3000
	s_nop 0
	v_addc_co_u32_e32 v55, vcc, 0, v21, vcc
	v_add_co_u32_e32 v56, vcc, s9, v20
	v_alignbit_b32 v15, v1, v0, 16
	s_nop 0
	v_addc_co_u32_e32 v57, vcc, 0, v21, vcc
	global_load_dwordx4 v[0:3], v[20:21], off
	global_load_dwordx4 v[4:7], v[22:23], off offset:1024
	global_load_dwordx4 v[8:11], v[54:55], off offset:2048
	global_load_dwordx4 v[58:61], v[56:57], off offset:3072
	s_ashr_i32 s9, s8, 31
	s_cmpk_lt_i32 s5, 0x30c0
	s_waitcnt vmcnt(2)
	v_mfma_f32_16x16x32_f16 v[4:7], v[4:7], v[12:15], 0
	v_mfma_f32_16x16x32_f16 v[0:3], v[0:3], v[12:15], 0
	s_waitcnt vmcnt(1)
	v_mfma_f32_16x16x32_f16 v[8:11], v[8:11], v[12:15], 0
	s_waitcnt vmcnt(0)
	v_mfma_f32_16x16x32_f16 v[12:15], v[58:61], v[12:15], 0
	global_load_dwordx4 v[58:61], v[18:19], off offset:64
	s_waitcnt vmcnt(0)
	v_cvt_f32_f16_e32 v62, v58
	v_cvt_f32_f16_sdwa v58, v58 dst_sel:DWORD dst_unused:UNUSED_PAD src0_sel:WORD_1
	v_mul_f32_e32 v62, 0xbfb8aa3b, v62
	v_exp_f32_e32 v62, v62
	v_mul_f32_e32 v58, 0xbfb8aa3b, v58
	v_add_f32_e32 v62, 1.0, v62
	s_nop 0
	v_rcp_f32_e32 v64, v62
	s_nop 0
	v_mul_f32_e32 v63, 1.0, v64
	v_mov_b32_e32 v62, v63
	v_cvt_f16_f32_e32 v64, v62
	v_exp_f32_e32 v62, v58
	v_cvt_f32_f16_e32 v58, v59
	v_cvt_f32_f16_sdwa v59, v59 dst_sel:DWORD dst_unused:UNUSED_PAD src0_sel:WORD_1
	v_mul_f32_e32 v58, 0xbfb8aa3b, v58
	v_exp_f32_e32 v63, v58
	v_mul_f32_e32 v59, 0xbfb8aa3b, v59
	v_pk_add_f32 v[62:63], v[62:63], 1.0 op_sel_hi:[1,0]
	s_nop 0
	s_nop 0
	v_rcp_f32_e32 v65, v63
	s_nop 0
	v_mul_f32_e32 v58, 1.0, v65
	s_nop 0
	v_rcp_f32_e32 v65, v62
	s_nop 0
	v_mul_f32_e32 v63, 1.0, v65
	v_mov_b32_e32 v62, v63
	v_cvt_pk_f16_f32 v65, v62, v58
	v_exp_f32_e32 v62, v59
	v_cvt_f32_f16_e32 v59, v60
	v_pack_b32_f16 v58, v64, v65
	v_cvt_f32_f16_sdwa v60, v60 dst_sel:DWORD dst_unused:UNUSED_PAD src0_sel:WORD_1
	v_mul_f32_e32 v59, 0xbfb8aa3b, v59
	v_exp_f32_e32 v63, v59
	v_mul_f32_e32 v60, 0xbfb8aa3b, v60
	v_pk_add_f32 v[62:63], v[62:63], 1.0 op_sel_hi:[1,0]
	s_nop 0
	s_nop 0
	v_rcp_f32_e32 v64, v63
	s_nop 0
	v_mul_f32_e32 v59, 1.0, v64
	s_nop 0
	v_rcp_f32_e32 v64, v62
	s_nop 0
	v_mul_f32_e32 v63, 1.0, v64
	v_mov_b32_e32 v62, v63
	v_cvt_pk_f16_f32 v64, v62, v59
	v_exp_f32_e32 v62, v60
	v_cvt_f32_f16_e32 v60, v61
	v_alignbit_b32 v59, v64, v65, 16
	v_cvt_f32_f16_sdwa v61, v61 dst_sel:DWORD dst_unused:UNUSED_PAD src0_sel:WORD_1
	v_mul_f32_e32 v60, 0xbfb8aa3b, v60
	v_exp_f32_e32 v63, v60
	v_mul_f32_e32 v61, 0xbfb8aa3b, v61
	v_exp_f32_e32 v61, v61
	v_pk_add_f32 v[62:63], v[62:63], 1.0 op_sel_hi:[1,0]
	s_nop 0
	v_add_f32_e32 v61, 1.0, v61
	v_rcp_f32_e32 v65, v63
	s_nop 0
	v_mul_f32_e32 v60, 1.0, v65
	s_nop 0
	v_rcp_f32_e32 v65, v62
	s_nop 0
	v_mul_f32_e32 v63, 1.0, v65
	v_mov_b32_e32 v62, v63
	v_cvt_pk_f16_f32 v62, v62, v60
	v_alignbit_b32 v60, v62, v64, 16
	s_nop 0
	v_rcp_f32_e32 v64, v61
	s_nop 0
	v_mul_f32_e32 v63, 1.0, v64
	v_mov_b32_e32 v61, v63
	v_cvt_f16_f32_e32 v61, v61
	v_alignbit_b32 v61, v61, v62, 16
	global_load_dwordx4 v[62:65], v[20:21], off offset:64
	global_load_dwordx4 v[244:247], v[22:23], off offset:1088
	global_load_dwordx4 v[248:251], v[54:55], off offset:2112
	global_load_dwordx4 v[252:255], v[56:57], off offset:3136
	s_waitcnt vmcnt(3)
; __device__ __forceinline__ float sigmoidf_(float x) { return 1.0f / (1.0f + __expf(-x)); }
; __device__ __forceinline__ void phase_readout(const Params& p, int l, float* smem) {
;     ...
; #pragma unroll
;     for (int ks = 0; ks < 5; ++ks) {
;       f16x8 xf = *(const f16x8*)(dGD + (size_t)row * 160 + ks * 32 + g * 8);
; #pragma unroll
;       for (int e = 0; e < 8; ++e) xf[e] = (f16)sigmoidf_((float)xf[e]);
; #pragma unroll
;       for (int nb = 0; nb < 4; ++nb) {
;         f16x8 wf = *(const f16x8*)(gwt + (size_t)(hh * HD + nb * 16 + lq) * 160 + ks * 32 + g * 8);
;         ga[nb] = __builtin_amdgcn_mfma_f32_16x16x32_f16(wf, xf, ga[nb], 0, 0, 0);
;       }
;     }
	v_mfma_f32_16x16x32_f16 v[0:3], v[62:65], v[58:61], v[0:3]
	s_waitcnt vmcnt(2)
	v_mfma_f32_16x16x32_f16 v[4:7], v[244:247], v[58:61], v[4:7]
	s_waitcnt vmcnt(1)
	v_mfma_f32_16x16x32_f16 v[8:11], v[248:251], v[58:61], v[8:11]
	s_waitcnt vmcnt(0)
	v_mfma_f32_16x16x32_f16 v[12:15], v[252:255], v[58:61], v[12:15]
	global_load_dwordx4 v[58:61], v[18:19], off offset:128
	s_waitcnt vmcnt(0)
	v_cvt_f32_f16_e32 v62, v58
	v_cvt_f32_f16_sdwa v58, v58 dst_sel:DWORD dst_unused:UNUSED_PAD src0_sel:WORD_1
	v_mul_f32_e32 v62, 0xbfb8aa3b, v62
	v_exp_f32_e32 v62, v62
	v_mul_f32_e32 v58, 0xbfb8aa3b, v58
	v_add_f32_e32 v62, 1.0, v62
	s_nop 0
	v_rcp_f32_e32 v64, v62
	s_nop 0
	v_mul_f32_e32 v63, 1.0, v64
	v_mov_b32_e32 v62, v63
	v_cvt_f16_f32_e32 v64, v62
	v_exp_f32_e32 v62, v58
	v_cvt_f32_f16_e32 v58, v59
	v_cvt_f32_f16_sdwa v59, v59 dst_sel:DWORD dst_unused:UNUSED_PAD src0_sel:WORD_1
	v_mul_f32_e32 v58, 0xbfb8aa3b, v58
	v_exp_f32_e32 v63, v58
	v_mul_f32_e32 v59, 0xbfb8aa3b, v59
	v_pk_add_f32 v[62:63], v[62:63], 1.0 op_sel_hi:[1,0]
	s_nop 0
	s_nop 0
	v_rcp_f32_e32 v65, v63
	s_nop 0
	v_mul_f32_e32 v58, 1.0, v65
	s_nop 0
	v_rcp_f32_e32 v65, v62
	s_nop 0
	v_mul_f32_e32 v63, 1.0, v65
	v_mov_b32_e32 v62, v63
	v_cvt_pk_f16_f32 v65, v62, v58
	v_exp_f32_e32 v62, v59
	v_cvt_f32_f16_e32 v59, v60
	v_pack_b32_f16 v58, v64, v65
	v_cvt_f32_f16_sdwa v60, v60 dst_sel:DWORD dst_unused:UNUSED_PAD src0_sel:WORD_1
	v_mul_f32_e32 v59, 0xbfb8aa3b, v59
	v_exp_f32_e32 v63, v59
	v_mul_f32_e32 v60, 0xbfb8aa3b, v60
	v_pk_add_f32 v[62:63], v[62:63], 1.0 op_sel_hi:[1,0]
	s_nop 0
	s_nop 0
	v_rcp_f32_e32 v64, v63
	s_nop 0
	v_mul_f32_e32 v59, 1.0, v64
	s_nop 0
	v_rcp_f32_e32 v64, v62
	s_nop 0
	v_mul_f32_e32 v63, 1.0, v64
	v_mov_b32_e32 v62, v63
	v_cvt_pk_f16_f32 v64, v62, v59
	v_exp_f32_e32 v62, v60
	v_cvt_f32_f16_e32 v60, v61
	v_alignbit_b32 v59, v64, v65, 16
	v_cvt_f32_f16_sdwa v61, v61 dst_sel:DWORD dst_unused:UNUSED_PAD src0_sel:WORD_1
	v_mul_f32_e32 v60, 0xbfb8aa3b, v60
	v_exp_f32_e32 v63, v60
	v_mul_f32_e32 v61, 0xbfb8aa3b, v61
	v_exp_f32_e32 v61, v61
	v_pk_add_f32 v[62:63], v[62:63], 1.0 op_sel_hi:[1,0]
	s_nop 0
	v_add_f32_e32 v61, 1.0, v61
	v_rcp_f32_e32 v65, v63
	s_nop 0
	v_mul_f32_e32 v60, 1.0, v65
	s_nop 0
	v_rcp_f32_e32 v65, v62
	s_nop 0
	v_mul_f32_e32 v63, 1.0, v65
	v_mov_b32_e32 v62, v63
	v_cvt_pk_f16_f32 v62, v62, v60
	v_alignbit_b32 v60, v62, v64, 16
	s_nop 0
	v_rcp_f32_e32 v64, v61
	s_nop 0
	v_mul_f32_e32 v63, 1.0, v64
	v_mov_b32_e32 v61, v63
	v_cvt_f16_f32_e32 v61, v61
	v_alignbit_b32 v61, v61, v62, 16
	global_load_dwordx4 v[62:65], v[20:21], off offset:128
	global_load_dwordx4 v[244:247], v[22:23], off offset:1152
	global_load_dwordx4 v[248:251], v[54:55], off offset:2176
	global_load_dwordx4 v[252:255], v[56:57], off offset:3200
	s_waitcnt vmcnt(3)
	v_mfma_f32_16x16x32_f16 v[0:3], v[62:65], v[58:61], v[0:3]
	s_waitcnt vmcnt(2)
	v_mfma_f32_16x16x32_f16 v[4:7], v[244:247], v[58:61], v[4:7]
	s_waitcnt vmcnt(1)
	v_mfma_f32_16x16x32_f16 v[8:11], v[248:251], v[58:61], v[8:11]
	s_waitcnt vmcnt(0)
	v_mfma_f32_16x16x32_f16 v[12:15], v[252:255], v[58:61], v[12:15]
	global_load_dwordx4 v[58:61], v[18:19], off offset:192
	s_waitcnt vmcnt(0)
	v_cvt_f32_f16_e32 v62, v58
	v_cvt_f32_f16_sdwa v58, v58 dst_sel:DWORD dst_unused:UNUSED_PAD src0_sel:WORD_1
	v_mul_f32_e32 v62, 0xbfb8aa3b, v62
	v_exp_f32_e32 v62, v62
	v_mul_f32_e32 v58, 0xbfb8aa3b, v58
	v_add_f32_e32 v62, 1.0, v62
	s_nop 0
	v_rcp_f32_e32 v64, v62
	s_nop 0
	v_mul_f32_e32 v63, 1.0, v64
	v_mov_b32_e32 v62, v63
	v_cvt_f16_f32_e32 v64, v62
	v_exp_f32_e32 v62, v58
	v_cvt_f32_f16_e32 v58, v59
	v_cvt_f32_f16_sdwa v59, v59 dst_sel:DWORD dst_unused:UNUSED_PAD src0_sel:WORD_1
	v_mul_f32_e32 v58, 0xbfb8aa3b, v58
	v_exp_f32_e32 v63, v58
	v_mul_f32_e32 v59, 0xbfb8aa3b, v59
	v_pk_add_f32 v[62:63], v[62:63], 1.0 op_sel_hi:[1,0]
	s_nop 0
	s_nop 0
	v_rcp_f32_e32 v65, v63
	s_nop 0
	v_mul_f32_e32 v58, 1.0, v65
	s_nop 0
	v_rcp_f32_e32 v65, v62
	s_nop 0
	v_mul_f32_e32 v63, 1.0, v65
	v_mov_b32_e32 v62, v63
	v_cvt_pk_f16_f32 v65, v62, v58
	v_exp_f32_e32 v62, v59
	v_cvt_f32_f16_e32 v59, v60
	v_pack_b32_f16 v58, v64, v65
	v_cvt_f32_f16_sdwa v60, v60 dst_sel:DWORD dst_unused:UNUSED_PAD src0_sel:WORD_1
	v_mul_f32_e32 v59, 0xbfb8aa3b, v59
	v_exp_f32_e32 v63, v59
	v_mul_f32_e32 v60, 0xbfb8aa3b, v60
	v_pk_add_f32 v[62:63], v[62:63], 1.0 op_sel_hi:[1,0]
	s_nop 0
	s_nop 0
	v_rcp_f32_e32 v64, v63
	s_nop 0
	v_mul_f32_e32 v59, 1.0, v64
	s_nop 0
	v_rcp_f32_e32 v64, v62
	s_nop 0
	v_mul_f32_e32 v63, 1.0, v64
	v_mov_b32_e32 v62, v63
	v_cvt_pk_f16_f32 v64, v62, v59
	v_exp_f32_e32 v62, v60
	v_cvt_f32_f16_e32 v60, v61
	v_alignbit_b32 v59, v64, v65, 16
	v_cvt_f32_f16_sdwa v61, v61 dst_sel:DWORD dst_unused:UNUSED_PAD src0_sel:WORD_1
	v_mul_f32_e32 v60, 0xbfb8aa3b, v60
	v_exp_f32_e32 v63, v60
	v_mul_f32_e32 v61, 0xbfb8aa3b, v61
	v_exp_f32_e32 v61, v61
	v_pk_add_f32 v[62:63], v[62:63], 1.0 op_sel_hi:[1,0]
	s_nop 0
	v_add_f32_e32 v61, 1.0, v61
	v_rcp_f32_e32 v65, v63
	s_nop 0
	v_mul_f32_e32 v60, 1.0, v65
	s_nop 0
	v_rcp_f32_e32 v65, v62
	s_nop 0
	v_mul_f32_e32 v63, 1.0, v65
	v_mov_b32_e32 v62, v63
	v_cvt_pk_f16_f32 v62, v62, v60
	v_alignbit_b32 v60, v62, v64, 16
	s_nop 0
	v_rcp_f32_e32 v64, v61
	s_nop 0
	v_mul_f32_e32 v63, 1.0, v64
	v_mov_b32_e32 v61, v63
	v_cvt_f16_f32_e32 v61, v61
	v_alignbit_b32 v61, v61, v62, 16
	global_load_dwordx4 v[62:65], v[20:21], off offset:192
	global_load_dwordx4 v[244:247], v[22:23], off offset:1216
	global_load_dwordx4 v[248:251], v[54:55], off offset:2240
	s_waitcnt vmcnt(2)
	v_mfma_f32_16x16x32_f16 v[0:3], v[62:65], v[58:61], v[0:3]
	s_waitcnt vmcnt(1)
	v_mfma_f32_16x16x32_f16 v[4:7], v[244:247], v[58:61], v[4:7]
	s_waitcnt vmcnt(0)
; __device__ __forceinline__ float sigmoidf_(float x) { return 1.0f / (1.0f + __expf(-x)); }
; __device__ __forceinline__ void phase_readout(const Params& p, int l, float* smem) {
;     ...
; #pragma unroll
;     for (int ks = 0; ks < 5; ++ks) {
;       f16x8 xf = *(const f16x8*)(dGD + (size_t)row * 160 + ks * 32 + g * 8);
; #pragma unroll
;       for (int e = 0; e < 8; ++e) xf[e] = (f16)sigmoidf_((float)xf[e]);
; #pragma unroll
;       for (int nb = 0; nb < 4; ++nb) {
;         f16x8 wf = *(const f16x8*)(gwt + (size_t)(hh * HD + nb * 16 + lq) * 160 + ks * 32 + g * 8);
;         ga[nb] = __builtin_amdgcn_mfma_f32_16x16x32_f16(wf, xf, ga[nb], 0, 0, 0);
;       }
;     }
;     float y[4][4];
;     float sum = 0.f;
; #pragma unroll
;     for (int nb = 0; nb < 4; ++nb) {
;       size_t o = (size_t)row * RD + hh * HD + nb * 16 + 4 * g;
;       uint2 ya = *(const uint2*)(Y0 + o), yb = *(const uint2*)(Y1 + o);
;       y[nb][0] = bf2f((unsigned short)(ya.x & 0xFFFFu)) + bf2f((unsigned short)(yb.x & 0xFFFFu));
;       y[nb][1] = bf2f((unsigned short)(ya.x >> 16)) + bf2f((unsigned short)(yb.x >> 16));
;       y[nb][2] = bf2f((unsigned short)(ya.y & 0xFFFFu)) + bf2f((unsigned short)(yb.y & 0xFFFFu));
;       y[nb][3] = bf2f((unsigned short)(ya.y >> 16)) + bf2f((unsigned short)(yb.y >> 16));
;       sum += (y[nb][0] + y[nb][1]) + (y[nb][2] + y[nb][3]);
;     }
;     sum += __shfl_xor(sum, 16, 64);
;     sum += __shfl_xor(sum, 32, 64);
;     const float mean = sum * (1.0f / 64.f);
	v_mfma_f32_16x16x32_f16 v[62:65], v[248:251], v[58:61], v[8:11]
	s_nop 2
	global_load_dwordx4 v[8:11], v[56:57], off offset:3264
	s_waitcnt vmcnt(0)
	v_mfma_f32_16x16x32_f16 v[58:61], v[8:11], v[58:61], v[12:15]
	global_load_dwordx4 v[8:11], v[18:19], off offset:256
	s_waitcnt vmcnt(0)
	s_nop 0
	v_cvt_f32_f16_e32 v12, v8
	v_cvt_f32_f16_sdwa v8, v8 dst_sel:DWORD dst_unused:UNUSED_PAD src0_sel:WORD_1
	v_mul_f32_e32 v12, 0xbfb8aa3b, v12
	v_exp_f32_e32 v12, v12
	v_mul_f32_e32 v8, 0xbfb8aa3b, v8
	v_add_f32_e32 v12, 1.0, v12
	s_nop 0
	v_rcp_f32_e32 v14, v12
	s_nop 0
	v_mul_f32_e32 v13, 1.0, v14
	v_mov_b32_e32 v12, v13
	v_cvt_f16_f32_e32 v14, v12
	v_exp_f32_e32 v12, v8
	v_cvt_f32_f16_e32 v8, v9
	v_mul_f32_e32 v8, 0xbfb8aa3b, v8
	v_exp_f32_e32 v13, v8
	s_nop 0
	v_pk_add_f32 v[12:13], v[12:13], 1.0 op_sel_hi:[1,0]
	s_nop 0
	s_nop 0
	v_rcp_f32_e32 v15, v13
	s_nop 0
	v_mul_f32_e32 v8, 1.0, v15
	s_nop 0
	v_rcp_f32_e32 v15, v12
	s_nop 0
	v_mul_f32_e32 v13, 1.0, v15
	v_mov_b32_e32 v12, v13
	v_cvt_pk_f16_f32 v12, v12, v8
	v_cvt_f32_f16_sdwa v8, v9 dst_sel:DWORD dst_unused:UNUSED_PAD src0_sel:WORD_1
	v_cvt_f32_f16_e32 v9, v10
	v_pack_b32_f16 v66, v14, v12
	v_mul_f32_e32 v8, 0xbfb8aa3b, v8
	v_mul_f32_e32 v9, 0xbfb8aa3b, v9
	v_exp_f32_e32 v8, v8
	v_exp_f32_e32 v9, v9
	s_nop 0
	v_pk_add_f32 v[8:9], v[8:9], 1.0 op_sel_hi:[1,0]
	s_nop 0
	s_nop 0
	v_rcp_f32_e32 v14, v9
	s_nop 0
	v_mul_f32_e32 v13, 1.0, v14
	v_mov_b32_e32 v9, v13
	s_nop 0
	v_rcp_f32_e32 v14, v8
	s_nop 0
	v_mul_f32_e32 v13, 1.0, v14
	v_mov_b32_e32 v8, v13
	v_cvt_pk_f16_f32 v13, v8, v9
	v_cvt_f32_f16_sdwa v8, v10 dst_sel:DWORD dst_unused:UNUSED_PAD src0_sel:WORD_1
	v_cvt_f32_f16_e32 v9, v11
	v_alignbit_b32 v67, v13, v12, 16
	v_mov_b32_e32 v19, s9
	v_mul_f32_e32 v8, 0xbfb8aa3b, v8
	v_mul_f32_e32 v9, 0xbfb8aa3b, v9
	v_exp_f32_e32 v8, v8
	v_exp_f32_e32 v9, v9
	s_nop 0
	v_pk_add_f32 v[8:9], v[8:9], 1.0 op_sel_hi:[1,0]
	s_nop 0
	s_nop 0
	v_rcp_f32_e32 v12, v9
	s_nop 0
	v_mul_f32_e32 v10, 1.0, v12
	v_mov_b32_e32 v9, v10
	s_nop 0
	v_rcp_f32_e32 v12, v8
	s_nop 0
	v_mul_f32_e32 v10, 1.0, v12
	v_mov_b32_e32 v8, v10
	v_cvt_pk_f16_f32 v8, v8, v9
	v_cvt_f32_f16_sdwa v9, v11 dst_sel:DWORD dst_unused:UNUSED_PAD src0_sel:WORD_1
	v_alignbit_b32 v68, v8, v13, 16
	v_mov_b32_e32 v18, s8
	v_mad_i64_i32 v[18:19], s[10:11], v16, s60, v[18:19]
	v_mul_f32_e32 v9, 0xbfb8aa3b, v9
	v_exp_f32_e32 v9, v9
	v_or_b32_e32 v18, v18, v44
	v_add_f32_e32 v9, 1.0, v9
	s_nop 0
	v_rcp_f32_e32 v11, v9
	s_nop 0
	v_mul_f32_e32 v10, 1.0, v11
	v_mov_b32_e32 v9, v10
	v_cvt_f16_f32_e32 v9, v9
	v_alignbit_b32 v69, v9, v8, 16
	global_load_dwordx4 v[8:11], v[20:21], off offset:256
	s_waitcnt vmcnt(0)
	v_mfma_f32_16x16x32_f16 v[12:15], v[8:11], v[66:69], v[0:3]
	s_nop 2
	global_load_dwordx4 v[0:3], v[22:23], off offset:1280
	v_lshlrev_b64 v[22:23], 1, v[18:19]
	v_lshl_add_u64 v[18:19], v[34:35], 0, v[22:23]
	s_waitcnt vmcnt(0)
	v_mfma_f32_16x16x32_f16 v[8:11], v[0:3], v[66:69], v[4:7]
	global_load_dwordx4 v[0:3], v[54:55], off offset:2304
	s_nop 0
	global_load_dwordx2 v[54:55], v[18:19], off
	v_lshl_add_u64 v[18:19], v[36:37], 0, v[22:23]
	s_waitcnt vmcnt(1)
	v_mfma_f32_16x16x32_f16 v[4:7], v[0:3], v[66:69], v[62:65]
	global_load_dwordx4 v[0:3], v[56:57], off offset:3328
	s_waitcnt vmcnt(1)
	v_lshlrev_b32_e32 v70, 16, v55
	global_load_dwordx2 v[56:57], v[18:19], off
	v_lshlrev_b32_e32 v18, 16, v54
	v_and_b32_e32 v19, 0xffff0000, v54
	v_and_b32_e32 v71, 0xffff0000, v55
	v_or_b32_e32 v54, 32, v22
	v_mov_b32_e32 v55, v23
	s_waitcnt vmcnt(1)
	v_mfma_f32_16x16x32_f16 v[0:3], v[0:3], v[66:69], v[58:61]
	s_waitcnt vmcnt(0)
	v_lshlrev_b32_e32 v20, 16, v56
	v_and_b32_e32 v21, 0xffff0000, v56
	v_lshlrev_b32_e32 v72, 16, v57
	v_and_b32_e32 v73, 0xffff0000, v57
	v_lshl_add_u64 v[56:57], v[34:35], 0, v[54:55]
	v_lshl_add_u64 v[54:55], v[36:37], 0, v[54:55]
	global_load_dwordx2 v[56:57], v[56:57], off
	s_nop 0
	global_load_dwordx2 v[54:55], v[54:55], off
	v_pk_add_f32 v[70:71], v[70:71], v[72:73]
	s_waitcnt vmcnt(1)
	v_lshlrev_b32_e32 v59, 16, v57
	v_lshlrev_b32_e32 v58, 16, v56
	s_waitcnt vmcnt(0)
	v_lshlrev_b32_e32 v61, 16, v55
	v_lshlrev_b32_e32 v60, 16, v54
	v_and_b32_e32 v57, 0xffff0000, v57
	v_and_b32_e32 v56, 0xffff0000, v56
	v_and_b32_e32 v55, 0xffff0000, v55
	v_and_b32_e32 v54, 0xffff0000, v54
	v_pk_add_f32 v[96:97], v[58:59], v[60:61]
	v_pk_add_f32 v[62:63], v[56:57], v[54:55]
	v_mov_b32_e32 v73, v70
	v_pk_add_f32 v[54:55], v[96:97], v[62:63]
	s_nop 0
	v_pk_add_f32 v[78:79], v[54:55], v[54:55] op_sel:[0,1] op_sel_hi:[1,0]
	v_or_b32_e32 v54, 64, v22
	v_mov_b32_e32 v55, v23
	v_lshl_add_u64 v[56:57], v[34:35], 0, v[54:55]
	v_lshl_add_u64 v[54:55], v[36:37], 0, v[54:55]
	global_load_dwordx2 v[56:57], v[56:57], off
	v_or_b32_e32 v22, 0x60, v22
	global_load_dwordx2 v[54:55], v[54:55], off
	s_waitcnt vmcnt(1)
	v_lshlrev_b32_e32 v58, 16, v56
	v_and_b32_e32 v59, 0xffff0000, v56
	s_waitcnt vmcnt(0)
	v_lshlrev_b32_e32 v60, 16, v54
	v_and_b32_e32 v61, 0xffff0000, v54
	v_lshlrev_b32_e32 v56, 16, v57
	v_lshlrev_b32_e32 v54, 16, v55
	v_and_b32_e32 v57, 0xffff0000, v57
	v_and_b32_e32 v55, 0xffff0000, v55
	v_pk_add_f32 v[60:61], v[58:59], v[60:61]
	v_pk_add_f32 v[58:59], v[56:57], v[54:55]
	v_lshl_add_u64 v[54:55], v[34:35], 0, v[22:23]
	v_lshl_add_u64 v[22:23], v[36:37], 0, v[22:23]
	global_load_dwordx2 v[22:23], v[22:23], off
	v_pk_add_f32 v[80:81], v[60:61], v[60:61] op_sel:[0,1] op_sel_hi:[1,0]
	global_load_dwordx2 v[54:55], v[54:55], off
	v_pk_add_f32 v[82:83], v[58:59], v[58:59] op_sel:[0,1] op_sel_hi:[1,0]
	s_waitcnt vmcnt(1)
	v_lshlrev_b32_e32 v87, 16, v22
	v_and_b32_e32 v86, 0xffff0000, v22
	v_lshlrev_b32_e32 v91, 16, v23
	v_and_b32_e32 v90, 0xffff0000, v23
	v_mad_i64_i32 v[22:23], s[8:9], v16, s60, v[100:101]
	v_lshlrev_b64 v[22:23], 1, v[22:23]
	s_waitcnt vmcnt(0)
; __device__ __forceinline__ void phase_readout(const Params& p, int l, float* smem) {
;     ...
;     float vv[4][4];
;     float bs = 0.f;
; #pragma unroll
;     for (int nb = 0; nb < 4; ++nb) {
;       const int c = hh * HD + nb * 16 + 4 * g;
;       size_t o = (size_t)row * RD + c;
;       f16x4 r4 = *(const f16x4*)(dR + o), k4 = *(const f16x4*)(dK + o), v4 = *(const f16x4*)(dV + o);
;       f16x4 a04 = *(const f16x4*)(dA0 + o), a14 = *(const f16x4*)(dA1 + o);
;       float4 rk = *(const float4*)(p.in[I_RK] + (size_t)l * RD + c);
;       float4 ka = *(const float4*)(p.in[I_KA] + (size_t)l * RD + c);
;       const float rkv[4] = {rk.x, rk.y, rk.z, rk.w}, kav[4] = {ka.x, ka.y, ka.z, ka.w};
; #pragma unroll
;       for (int i = 0; i < 4; ++i) {
;         float kds = (float)k4[i] * (2.0f + ((float)a04[i] + (float)a14[i] - 2.0f) * kav[i]);
;         bs += (float)r4[i] * rkv[i] * kds;
;         vv[nb][i] = (float)v4[i];
;       }
;     }
;     bs += __shfl_xor(bs, 16, 64);
;     bs += __shfl_xor(bs, 32, 64);
	v_lshlrev_b32_e32 v85, 16, v54
	v_and_b32_e32 v84, 0xffff0000, v54
	v_lshlrev_b32_e32 v89, 16, v55
	v_and_b32_e32 v88, 0xffff0000, v55
	v_lshl_add_u64 v[54:55], v[24:25], 0, v[22:23]
	global_load_dwordx2 v[68:69], v[54:55], off
	v_lshl_add_u64 v[54:55], v[26:27], 0, v[22:23]
	global_load_dwordx2 v[76:77], v[54:55], off
	v_lshl_add_u64 v[54:55], v[28:29], 0, v[22:23]
	global_load_dwordx2 v[74:75], v[54:55], off
	v_lshl_add_u64 v[54:55], v[30:31], 0, v[22:23]
	v_lshl_add_u64 v[22:23], v[32:33], 0, v[22:23]
	global_load_dwordx2 v[92:93], v[54:55], off
	global_load_dwordx2 v[98:99], v[22:23], off
	v_lshlrev_b64 v[22:23], 2, v[100:101]
	v_lshl_add_u64 v[104:105], v[48:49], 0, v[22:23]
	global_load_dwordx4 v[64:67], v[104:105], off
	v_lshl_add_u64 v[102:103], v[46:47], 0, v[22:23]
	global_load_dwordx4 v[54:57], v[102:103], off
	v_pk_add_f32 v[84:85], v[84:85], v[86:87]
	s_waitcnt vmcnt(5)
	v_cvt_f32_f16_e32 v79, v76
	s_waitcnt vmcnt(3)
	v_cvt_f32_f16_e32 v81, v92
	s_waitcnt vmcnt(2)
	v_cvt_f32_f16_e32 v83, v98
	v_add_f32_e32 v81, v81, v83
	v_add_f32_e32 v81, -2.0, v81
	s_waitcnt vmcnt(1)
	v_fma_f32 v64, v81, v64, 2.0
	v_mul_f32_e32 v64, v64, v79
	v_cvt_f32_f16_e32 v79, v68
	s_waitcnt vmcnt(0)
	v_mul_f32_e32 v54, v54, v79
	v_fma_f32 v79, v54, v64, 0
	v_cvt_f32_f16_sdwa v54, v76 dst_sel:DWORD dst_unused:UNUSED_PAD src0_sel:WORD_1
	v_cvt_f32_f16_sdwa v64, v92 dst_sel:DWORD dst_unused:UNUSED_PAD src0_sel:WORD_1
	v_cvt_f32_f16_sdwa v76, v98 dst_sel:DWORD dst_unused:UNUSED_PAD src0_sel:WORD_1
	v_add_f32_e32 v64, v64, v76
	v_add_f32_e32 v64, -2.0, v64
	v_fma_f32 v64, v64, v65, 2.0
	v_mul_f32_e32 v54, v64, v54
	v_cvt_f32_f16_sdwa v64, v68 dst_sel:DWORD dst_unused:UNUSED_PAD src0_sel:WORD_1
	v_mul_f32_e32 v55, v55, v64
	v_fmac_f32_e32 v79, v55, v54
	v_cvt_f32_f16_e32 v55, v93
	v_cvt_f32_f16_e32 v64, v99
	v_cvt_f32_f16_e32 v54, v77
	v_add_f32_e32 v55, v55, v64
	v_add_f32_e32 v55, -2.0, v55
	v_fma_f32 v55, v55, v66, 2.0
	v_mul_f32_e32 v54, v55, v54
	v_cvt_f32_f16_e32 v55, v69
	v_mul_f32_e32 v55, v56, v55
	v_fmac_f32_e32 v79, v55, v54
	v_cvt_f32_f16_sdwa v55, v93 dst_sel:DWORD dst_unused:UNUSED_PAD src0_sel:WORD_1
	v_cvt_f32_f16_sdwa v56, v99 dst_sel:DWORD dst_unused:UNUSED_PAD src0_sel:WORD_1
	v_cvt_f32_f16_sdwa v54, v77 dst_sel:DWORD dst_unused:UNUSED_PAD src0_sel:WORD_1
	v_add_f32_e32 v55, v55, v56
	v_add_f32_e32 v55, -2.0, v55
	v_fma_f32 v55, v55, v67, 2.0
	v_mul_f32_e32 v54, v55, v54
	v_cvt_f32_f16_sdwa v55, v69 dst_sel:DWORD dst_unused:UNUSED_PAD src0_sel:WORD_1
	v_mul_f32_e32 v55, v57, v55
	v_fmac_f32_e32 v79, v55, v54
	v_add_u32_e32 v54, 16, v100
	v_ashrrev_i32_e32 v55, 31, v54
	v_mad_i64_i32 v[54:55], s[8:9], v16, s60, v[54:55]
	v_lshlrev_b64 v[54:55], 1, v[54:55]
	v_lshl_add_u64 v[56:57], v[24:25], 0, v[54:55]
	global_load_dwordx2 v[68:69], v[56:57], off
	v_lshl_add_u64 v[56:57], v[26:27], 0, v[54:55]
	global_load_dwordx2 v[76:77], v[56:57], off
	v_lshl_add_u64 v[56:57], v[28:29], 0, v[54:55]
	global_load_dwordx2 v[98:99], v[56:57], off
	v_lshl_add_u64 v[56:57], v[30:31], 0, v[54:55]
	global_load_dwordx2 v[92:93], v[56:57], off
	v_lshl_add_u64 v[54:55], v[32:33], 0, v[54:55]
	global_load_dwordx2 v[108:109], v[54:55], off
	s_nop 0
	global_load_dwordx4 v[54:57], v[102:103], off offset:64
	global_load_dwordx4 v[64:67], v[104:105], off offset:64
	s_waitcnt vmcnt(5)
	v_cvt_f32_f16_e32 v81, v76
	s_waitcnt vmcnt(3)
	v_cvt_f32_f16_e32 v83, v92
	s_waitcnt vmcnt(2)
	v_cvt_f32_f16_e32 v94, v108
	v_add_f32_e32 v83, v83, v94
	v_add_f32_e32 v83, -2.0, v83
	s_waitcnt vmcnt(0)
	v_fma_f32 v64, v83, v64, 2.0
	v_mul_f32_e32 v64, v64, v81
	v_cvt_f32_f16_e32 v81, v68
	v_mul_f32_e32 v54, v54, v81
	v_fmac_f32_e32 v79, v54, v64
	v_cvt_f32_f16_sdwa v54, v76 dst_sel:DWORD dst_unused:UNUSED_PAD src0_sel:WORD_1
	v_cvt_f32_f16_sdwa v64, v92 dst_sel:DWORD dst_unused:UNUSED_PAD src0_sel:WORD_1
	v_cvt_f32_f16_sdwa v76, v108 dst_sel:DWORD dst_unused:UNUSED_PAD src0_sel:WORD_1
	v_add_f32_e32 v64, v64, v76
	v_add_f32_e32 v64, -2.0, v64
	v_fma_f32 v64, v64, v65, 2.0
	v_mul_f32_e32 v54, v64, v54
	v_cvt_f32_f16_sdwa v64, v68 dst_sel:DWORD dst_unused:UNUSED_PAD src0_sel:WORD_1
	v_cvt_f32_f16_sdwa v65, v93 dst_sel:DWORD dst_unused:UNUSED_PAD src0_sel:WORD_1
	v_cvt_f32_f16_e32 v76, v109
	v_mul_f32_e32 v55, v55, v64
	v_fmac_f32_e32 v79, v55, v54
	v_cvt_f32_f16_e32 v54, v77
	v_cvt_f32_f16_sdwa v55, v77 dst_sel:DWORD dst_unused:UNUSED_PAD src0_sel:WORD_1
	v_cvt_f32_f16_e32 v64, v93
	v_cvt_f32_f16_sdwa v77, v109 dst_sel:DWORD dst_unused:UNUSED_PAD src0_sel:WORD_1
	v_pk_add_f32 v[64:65], v[64:65], v[76:77]
	s_nop 0
	v_pk_add_f32 v[64:65], v[64:65], -2.0 op_sel_hi:[1,0]
	s_nop 0
	v_pk_fma_f32 v[64:65], v[64:65], v[66:67], 2.0 op_sel_hi:[1,1,0]
	s_nop 0
	v_pk_mul_f32 v[54:55], v[64:65], v[54:55]
	v_cvt_f32_f16_e32 v64, v69
	v_cvt_f32_f16_sdwa v65, v69 dst_sel:DWORD dst_unused:UNUSED_PAD src0_sel:WORD_1
	v_pk_mul_f32 v[56:57], v[56:57], v[64:65]
	s_nop 0
	v_pk_mul_f32 v[54:55], v[56:57], v[54:55]
	s_nop 0
	v_add_f32_e32 v54, v79, v54
	v_add_f32_e32 v79, v54, v55
	v_add_u32_e32 v54, 32, v100
	v_ashrrev_i32_e32 v55, 31, v54
	v_mad_i64_i32 v[54:55], s[8:9], v16, s60, v[54:55]
	v_lshlrev_b64 v[54:55], 1, v[54:55]
	v_lshl_add_u64 v[56:57], v[24:25], 0, v[54:55]
	global_load_dwordx2 v[76:77], v[56:57], off
	v_lshl_add_u64 v[56:57], v[26:27], 0, v[54:55]
	global_load_dwordx2 v[92:93], v[56:57], off
	v_lshl_add_u64 v[56:57], v[28:29], 0, v[54:55]
	global_load_dwordx2 v[64:65], v[56:57], off
	v_lshl_add_u64 v[56:57], v[30:31], 0, v[54:55]
	global_load_dwordx2 v[108:109], v[56:57], off
	v_lshl_add_u64 v[54:55], v[32:33], 0, v[54:55]
	global_load_dwordx2 v[110:111], v[54:55], off
	s_nop 0
	global_load_dwordx4 v[54:57], v[102:103], off offset:128
	global_load_dwordx4 v[66:69], v[104:105], off offset:128
	s_waitcnt vmcnt(5)
; __device__ __forceinline__ void phase_readout(const Params& p, int l, float* smem) {
;     ...
;     float y[4][4];
;     float sum = 0.f;
; #pragma unroll
;     for (int nb = 0; nb < 4; ++nb) {
;       size_t o = (size_t)row * RD + hh * HD + nb * 16 + 4 * g;
;       uint2 ya = *(const uint2*)(Y0 + o), yb = *(const uint2*)(Y1 + o);
;       y[nb][0] = bf2f((unsigned short)(ya.x & 0xFFFFu)) + bf2f((unsigned short)(yb.x & 0xFFFFu));
;       y[nb][1] = bf2f((unsigned short)(ya.x >> 16)) + bf2f((unsigned short)(yb.x >> 16));
;       y[nb][2] = bf2f((unsigned short)(ya.y & 0xFFFFu)) + bf2f((unsigned short)(yb.y & 0xFFFFu));
;       y[nb][3] = bf2f((unsigned short)(ya.y >> 16)) + bf2f((unsigned short)(yb.y >> 16));
;       sum += (y[nb][0] + y[nb][1]) + (y[nb][2] + y[nb][3]);
;     }
;     sum += __shfl_xor(sum, 16, 64);
;     sum += __shfl_xor(sum, 32, 64);
;     const float mean = sum * (1.0f / 64.f);
;     float vs = 0.f;
; #pragma unroll
;     for (int nb = 0; nb < 4; ++nb)
; #pragma unroll
;       for (int i = 0; i < 4; ++i) { y[nb][i] -= mean; vs += y[nb][i] * y[nb][i]; }
;     vs += __shfl_xor(vs, 16, 64);
;     vs += __shfl_xor(vs, 32, 64);
;     const float rstd = rsqrtf(vs * (1.0f / 64.f) + 64e-5f);
;     float vv[4][4];
;     float bs = 0.f;
; #pragma unroll
;     for (int nb = 0; nb < 4; ++nb) {
;       const int c = hh * HD + nb * 16 + 4 * g;
;       size_t o = (size_t)row * RD + c;
;       f16x4 r4 = *(const f16x4*)(dR + o), k4 = *(const f16x4*)(dK + o), v4 = *(const f16x4*)(dV + o);
;       f16x4 a04 = *(const f16x4*)(dA0 + o), a14 = *(const f16x4*)(dA1 + o);
;       float4 rk = *(const float4*)(p.in[I_RK] + (size_t)l * RD + c);
;       float4 ka = *(const float4*)(p.in[I_KA] + (size_t)l * RD + c);
;       const float rkv[4] = {rk.x, rk.y, rk.z, rk.w}, kav[4] = {ka.x, ka.y, ka.z, ka.w};
; #pragma unroll
;       for (int i = 0; i < 4; ++i) {
;         float kds = (float)k4[i] * (2.0f + ((float)a04[i] + (float)a14[i] - 2.0f) * kav[i]);
;         bs += (float)r4[i] * rkv[i] * kds;
;         vv[nb][i] = (float)v4[i];
;       }
;     }
;     bs += __shfl_xor(bs, 16, 64);
;     bs += __shfl_xor(bs, 32, 64);
; #pragma unroll
;     for (int nb = 0; nb < 4; ++nb) {
;       const int c = hh * HD + nb * 16 + 4 * g;
;       float4 gwv = *(const float4*)(p.in[I_GNW] + (size_t)l * RD + c);
;       float4 gbv = *(const float4*)(p.in[I_GNB] + (size_t)l * RD + c);
	v_cvt_f32_f16_e32 v112, v92
	v_cvt_f32_f16_sdwa v113, v92 dst_sel:DWORD dst_unused:UNUSED_PAD src0_sel:WORD_1
	s_waitcnt vmcnt(3)
	v_cvt_f32_f16_e32 v114, v108
	v_cvt_f32_f16_sdwa v115, v108 dst_sel:DWORD dst_unused:UNUSED_PAD src0_sel:WORD_1
	s_waitcnt vmcnt(2)
	v_cvt_f32_f16_e32 v116, v110
	v_cvt_f32_f16_sdwa v117, v110 dst_sel:DWORD dst_unused:UNUSED_PAD src0_sel:WORD_1
	v_cvt_f32_f16_e32 v92, v111
	v_pk_add_f32 v[114:115], v[114:115], v[116:117]
	s_nop 0
	v_pk_add_f32 v[114:115], v[114:115], -2.0 op_sel_hi:[1,0]
	s_waitcnt vmcnt(0)
	v_pk_fma_f32 v[66:67], v[114:115], v[66:67], 2.0 op_sel_hi:[1,1,0]
	s_nop 0
	v_pk_mul_f32 v[66:67], v[66:67], v[112:113]
	v_cvt_f32_f16_e32 v112, v76
	v_cvt_f32_f16_sdwa v113, v76 dst_sel:DWORD dst_unused:UNUSED_PAD src0_sel:WORD_1
	v_pk_mul_f32 v[54:55], v[54:55], v[112:113]
	s_nop 0
	v_pk_mul_f32 v[54:55], v[54:55], v[66:67]
	v_cvt_f32_f16_e32 v66, v109
	v_add_f32_e32 v54, v79, v54
	v_add_f32_e32 v76, v54, v55
	v_cvt_f32_f16_e32 v54, v93
	v_cvt_f32_f16_sdwa v55, v93 dst_sel:DWORD dst_unused:UNUSED_PAD src0_sel:WORD_1
	v_cvt_f32_f16_sdwa v67, v109 dst_sel:DWORD dst_unused:UNUSED_PAD src0_sel:WORD_1
	v_cvt_f32_f16_sdwa v93, v111 dst_sel:DWORD dst_unused:UNUSED_PAD src0_sel:WORD_1
	v_pk_add_f32 v[66:67], v[66:67], v[92:93]
	s_nop 0
	v_pk_add_f32 v[66:67], v[66:67], -2.0 op_sel_hi:[1,0]
	s_nop 0
	v_pk_fma_f32 v[66:67], v[66:67], v[68:69], 2.0 op_sel_hi:[1,1,0]
	s_nop 0
	v_pk_mul_f32 v[54:55], v[66:67], v[54:55]
	v_cvt_f32_f16_e32 v66, v77
	v_cvt_f32_f16_sdwa v67, v77 dst_sel:DWORD dst_unused:UNUSED_PAD src0_sel:WORD_1
	v_pk_mul_f32 v[56:57], v[56:57], v[66:67]
	s_nop 0
	v_pk_mul_f32 v[54:55], v[56:57], v[54:55]
	s_nop 0
	v_add_f32_e32 v54, v76, v54
	v_add_f32_e32 v79, v54, v55
	v_add_u32_e32 v54, 48, v100
	v_ashrrev_i32_e32 v55, 31, v54
	v_mad_i64_i32 v[54:55], s[8:9], v16, s60, v[54:55]
	v_lshlrev_b64 v[56:57], 1, v[54:55]
	v_lshl_add_u64 v[54:55], v[24:25], 0, v[56:57]
	v_lshl_add_u64 v[66:67], v[30:31], 0, v[56:57]
	global_load_dwordx2 v[76:77], v[54:55], off
	v_lshl_add_u64 v[54:55], v[26:27], 0, v[56:57]
	global_load_dwordx2 v[108:109], v[66:67], off
	global_load_dwordx2 v[92:93], v[54:55], off
	v_lshl_add_u64 v[54:55], v[28:29], 0, v[56:57]
	v_lshl_add_u64 v[56:57], v[32:33], 0, v[56:57]
	global_load_dwordx2 v[54:55], v[54:55], off
	s_nop 0
	global_load_dwordx2 v[56:57], v[56:57], off
	s_nop 0
	global_load_dwordx4 v[66:69], v[102:103], off offset:192
	s_nop 0
	global_load_dwordx4 v[102:105], v[104:105], off offset:192
	v_lshlrev_b64 v[16:17], 11, v[16:17]
	s_mul_i32 s8, s28, 0x2800
	v_add_u32_e32 v107, s8, v107
	s_waitcnt vmcnt(5)
	v_cvt_f32_f16_e32 v112, v108
	v_cvt_f32_f16_sdwa v113, v108 dst_sel:DWORD dst_unused:UNUSED_PAD src0_sel:WORD_1
	s_waitcnt vmcnt(4)
	v_cvt_f32_f16_e32 v110, v92
	s_waitcnt vmcnt(2)
	v_cvt_f32_f16_e32 v114, v56
	v_cvt_f32_f16_sdwa v115, v56 dst_sel:DWORD dst_unused:UNUSED_PAD src0_sel:WORD_1
	v_cvt_f32_f16_sdwa v111, v92 dst_sel:DWORD dst_unused:UNUSED_PAD src0_sel:WORD_1
	v_cvt_f32_f16_e32 v92, v109
	v_pk_add_f32 v[112:113], v[112:113], v[114:115]
	s_nop 0
	v_pk_add_f32 v[112:113], v[112:113], -2.0 op_sel_hi:[1,0]
	s_waitcnt vmcnt(0)
	v_pk_fma_f32 v[102:103], v[112:113], v[102:103], 2.0 op_sel_hi:[1,1,0]
	s_nop 0
	v_pk_mul_f32 v[102:103], v[102:103], v[110:111]
	v_cvt_f32_f16_e32 v110, v76
	v_cvt_f32_f16_sdwa v111, v76 dst_sel:DWORD dst_unused:UNUSED_PAD src0_sel:WORD_1
	v_pk_mul_f32 v[66:67], v[66:67], v[110:111]
	s_nop 0
	v_pk_mul_f32 v[66:67], v[66:67], v[102:103]
	v_lshl_add_u64 v[102:103], v[38:39], 0, v[16:17]
	v_add_f32_e32 v56, v79, v66
	v_add_f32_e32 v76, v56, v67
	v_cvt_f32_f16_e32 v66, v93
	v_cvt_f32_f16_sdwa v67, v93 dst_sel:DWORD dst_unused:UNUSED_PAD src0_sel:WORD_1
	v_cvt_f32_f16_sdwa v93, v109 dst_sel:DWORD dst_unused:UNUSED_PAD src0_sel:WORD_1
	v_cvt_f32_f16_e32 v56, v57
	v_cvt_f32_f16_sdwa v57, v57 dst_sel:DWORD dst_unused:UNUSED_PAD src0_sel:WORD_1
	v_mov_b32_e32 v79, v84
	v_pk_add_f32 v[56:57], v[92:93], v[56:57]
	s_nop 0
	v_pk_add_f32 v[56:57], v[56:57], -2.0 op_sel_hi:[1,0]
	v_pk_add_f32 v[92:93], v[18:19], v[20:21]
	v_pk_fma_f32 v[56:57], v[56:57], v[104:105], 2.0 op_sel_hi:[1,1,0]
	v_mov_b32_e32 v72, v92
	v_pk_mul_f32 v[56:57], v[56:57], v[66:67]
	v_cvt_f32_f16_e32 v66, v77
	v_cvt_f32_f16_sdwa v67, v77 dst_sel:DWORD dst_unused:UNUSED_PAD src0_sel:WORD_1
	v_mov_b32_e32 v104, v93
	v_mov_b32_e32 v105, v71
	v_pk_add_f32 v[72:73], v[72:73], v[104:105]
	v_pk_mul_f32 v[66:67], v[68:69], v[66:67]
	v_lshl_add_u64 v[68:69], v[50:51], 0, v[22:23]
	v_pk_mul_f32 v[56:57], v[66:67], v[56:57]
	v_lshl_add_u64 v[66:67], v[52:53], 0, v[22:23]
	global_load_dwordx4 v[16:19], v[68:69], off
	global_load_dwordx4 v[20:23], v[66:67], off
	v_add_f32_e32 v56, v76, v56
	v_add_f32_e32 v56, v56, v57
	ds_bpermute_b32 v57, v95, v56
	v_pk_add_f32 v[104:105], v[88:89], v[90:91]
	v_cvt_f32_f16_e32 v76, v74
	v_mov_b32_e32 v81, v105
	v_mov_b32_e32 v83, v104
	s_waitcnt lgkmcnt(0)
	v_add_f32_e32 v56, v56, v57
	ds_bpermute_b32 v57, v106, v56
	v_pk_add_f32 v[80:81], v[80:81], v[82:83]
	v_cvt_f32_f16_sdwa v77, v74 dst_sel:DWORD dst_unused:UNUSED_PAD src0_sel:WORD_1
	v_cvt_f32_f16_e32 v74, v75
	v_cvt_f32_f16_sdwa v75, v75 dst_sel:DWORD dst_unused:UNUSED_PAD src0_sel:WORD_1
	s_waitcnt lgkmcnt(0)
	v_add_f32_e32 v56, v56, v57
	v_add_f32_e32 v57, v72, v73
	v_add_f32_e32 v72, 0, v57
	v_mov_b32_e32 v73, v85
	v_pk_add_f32 v[72:73], v[72:73], v[78:79]
	s_nop 0
	v_pk_add_f32 v[72:73], v[72:73], v[80:81]
	v_lshl_add_u64 v[80:81], v[100:101], 1, v[102:103]
	v_add_f32_e32 v57, v72, v73
	ds_bpermute_b32 v72, v95, v57
	v_mov_b32_e32 v100, v96
	v_mov_b32_e32 v101, v62
	v_mov_b32_e32 v62, v97
	s_waitcnt lgkmcnt(0)
; __device__ __forceinline__ void phase_readout(const Params& p, int l, float* smem) {
;     ...
;     sum += __shfl_xor(sum, 16, 64);
;     sum += __shfl_xor(sum, 32, 64);
;     const float mean = sum * (1.0f / 64.f);
;     float vs = 0.f;
; #pragma unroll
;     for (int nb = 0; nb < 4; ++nb)
; #pragma unroll
;       for (int i = 0; i < 4; ++i) { y[nb][i] -= mean; vs += y[nb][i] * y[nb][i]; }
;     vs += __shfl_xor(vs, 16, 64);
;     vs += __shfl_xor(vs, 32, 64);
;     const float rstd = rsqrtf(vs * (1.0f / 64.f) + 64e-5f);
;     float vv[4][4];
;     float bs = 0.f;
; #pragma unroll
;     for (int nb = 0; nb < 4; ++nb) {
;       const int c = hh * HD + nb * 16 + 4 * g;
;       size_t o = (size_t)row * RD + c;
;       f16x4 r4 = *(const f16x4*)(dR + o), k4 = *(const f16x4*)(dK + o), v4 = *(const f16x4*)(dV + o);
;       f16x4 a04 = *(const f16x4*)(dA0 + o), a14 = *(const f16x4*)(dA1 + o);
;       float4 rk = *(const float4*)(p.in[I_RK] + (size_t)l * RD + c);
;       float4 ka = *(const float4*)(p.in[I_KA] + (size_t)l * RD + c);
;       const float rkv[4] = {rk.x, rk.y, rk.z, rk.w}, kav[4] = {ka.x, ka.y, ka.z, ka.w};
; #pragma unroll
;       for (int i = 0; i < 4; ++i) {
;         float kds = (float)k4[i] * (2.0f + ((float)a04[i] + (float)a14[i] - 2.0f) * kav[i]);
;         bs += (float)r4[i] * rkv[i] * kds;
;         vv[nb][i] = (float)v4[i];
;       }
;     }
;     bs += __shfl_xor(bs, 16, 64);
;     bs += __shfl_xor(bs, 32, 64);
; #pragma unroll
;     for (int nb = 0; nb < 4; ++nb) {
;       const int c = hh * HD + nb * 16 + 4 * g;
;       float4 gwv = *(const float4*)(p.in[I_GNW] + (size_t)l * RD + c);
;       float4 gbv = *(const float4*)(p.in[I_GNB] + (size_t)l * RD + c);
;       const float gwa[4] = {gwv.x, gwv.y, gwv.z, gwv.w}, gba[4] = {gbv.x, gbv.y, gbv.z, gbv.w};
;       f16x4 o4;
; #pragma unroll
;       for (int i = 0; i < 4; ++i) o4[i] = (f16)((y[nb][i] * rstd * gwa[i] + gba[i] + bs * vv[nb][i]) * ga[nb][i]);
;       *(f16x4*)(br + (size_t)row * DM + c) = o4;
;     }
	v_add_f32_e32 v57, v57, v72
	ds_bpermute_b32 v72, v106, v57
	s_waitcnt lgkmcnt(0)
	v_add_f32_e32 v57, v57, v72
	v_mul_f32_e32 v94, 0x3c800000, v57
	v_pk_add_f32 v[82:83], v[92:93], v[94:95] op_sel_hi:[1,0] neg_lo:[0,1] neg_hi:[0,1]
	v_pk_add_f32 v[78:79], v[70:71], v[94:95] op_sel_hi:[1,0] neg_lo:[0,1] neg_hi:[0,1]
	v_pk_mul_f32 v[92:93], v[82:83], v[82:83]
	v_pk_mul_f32 v[90:91], v[78:79], v[78:79]
	v_add_f32_e32 v57, v92, v93
	v_pk_add_f32 v[100:101], v[100:101], v[94:95] op_sel_hi:[1,0] neg_lo:[0,1] neg_hi:[0,1]
	v_add_f32_e32 v57, v90, v57
	v_pk_mul_f32 v[102:103], v[100:101], v[100:101]
	v_add_f32_e32 v57, v91, v57
	v_pk_add_f32 v[70:71], v[104:105], v[94:95] op_sel_hi:[1,0] neg_lo:[0,1] neg_hi:[0,1]
	v_pk_add_f32 v[104:105], v[62:63], v[94:95] op_sel_hi:[1,0] neg_lo:[0,1] neg_hi:[0,1]
	v_add_f32_e32 v57, v102, v57
	v_pk_mul_f32 v[108:109], v[104:105], v[104:105]
	v_add_f32_e32 v57, v103, v57
	v_pk_add_f32 v[96:97], v[60:61], v[94:95] op_sel_hi:[1,0] neg_lo:[0,1] neg_hi:[0,1]
	v_add_f32_e32 v57, v108, v57
	v_pk_mul_f32 v[110:111], v[96:97], v[96:97]
	v_add_f32_e32 v57, v109, v57
	v_pk_add_f32 v[58:59], v[58:59], v[94:95] op_sel_hi:[1,0] neg_lo:[0,1] neg_hi:[0,1]
	v_add_f32_e32 v57, v110, v57
	v_cvt_f32_f16_e32 v62, v64
	v_cvt_f32_f16_sdwa v63, v64 dst_sel:DWORD dst_unused:UNUSED_PAD src0_sel:WORD_1
	v_cvt_f32_f16_e32 v60, v65
	v_cvt_f32_f16_sdwa v61, v65 dst_sel:DWORD dst_unused:UNUSED_PAD src0_sel:WORD_1
	v_pk_mul_f32 v[64:65], v[58:59], v[58:59]
	v_add_f32_e32 v57, v111, v57
	v_pk_add_f32 v[72:73], v[84:85], v[94:95] op_sel_hi:[1,0] neg_lo:[0,1] neg_hi:[0,1]
	v_add_f32_e32 v57, v64, v57
	v_pk_mul_f32 v[88:89], v[72:73], v[72:73]
	v_add_f32_e32 v57, v65, v57
	v_add_f32_e32 v57, v89, v57
	v_pk_mul_f32 v[86:87], v[70:71], v[70:71]
	v_add_f32_e32 v57, v88, v57
	v_add_f32_e32 v57, v87, v57
	v_add_f32_e32 v57, v86, v57
	ds_bpermute_b32 v64, v95, v57
	v_cvt_f32_f16_e32 v84, v98
	v_cvt_f32_f16_sdwa v85, v98 dst_sel:DWORD dst_unused:UNUSED_PAD src0_sel:WORD_1
	v_cvt_f32_f16_e32 v98, v99
	v_cvt_f32_f16_sdwa v99, v99 dst_sel:DWORD dst_unused:UNUSED_PAD src0_sel:WORD_1
	s_waitcnt lgkmcnt(0)
	v_add_f32_e32 v57, v57, v64
	ds_bpermute_b32 v64, v106, v57
	s_waitcnt lgkmcnt(0)
	v_add_f32_e32 v57, v57, v64
	v_fmamk_f32 v57, v57, 0x3c800000, v178
	v_cmp_gt_f32_e32 vcc, s83, v57
	v_mul_f32_e32 v64, 0x4b800000, v57
	s_nop 0
	v_cndmask_b32_e32 v57, v57, v64, vcc
	v_rsq_f32_e32 v57, v57
	s_nop 0
	v_mul_f32_e32 v64, 0x45800000, v57
	v_cndmask_b32_e32 v64, v57, v64, vcc
	v_pk_mul_f32 v[82:83], v[82:83], v[64:65] op_sel_hi:[1,0]
	s_waitcnt vmcnt(0)
	v_pk_fma_f32 v[16:17], v[82:83], v[16:17], v[20:21]
	v_pk_mul_f32 v[20:21], v[100:101], v[64:65] op_sel_hi:[1,0]
	v_pk_fma_f32 v[16:17], v[56:57], v[76:77], v[16:17] op_sel_hi:[0,1,1]
	v_pk_mul_f32 v[12:13], v[12:13], v[16:17]
	v_pk_mul_f32 v[16:17], v[78:79], v[64:65] op_sel_hi:[1,0]
	v_cvt_pk_f16_f32 v12, v12, v13
	v_pk_fma_f32 v[16:17], v[16:17], v[18:19], v[22:23]
	s_nop 0
	v_pk_fma_f32 v[16:17], v[56:57], v[74:75], v[16:17] op_sel_hi:[0,1,1]
	v_pk_mul_f32 v[14:15], v[14:15], v[16:17]
	s_nop 0
	v_cvt_pk_f16_f32 v13, v14, v15
	global_store_dwordx2 v[80:81], v[12:13], off
	global_load_dwordx4 v[12:15], v[68:69], off offset:64
	s_nop 0
	global_load_dwordx4 v[16:19], v[66:67], off offset:64
	s_waitcnt vmcnt(0)
	v_pk_fma_f32 v[12:13], v[20:21], v[12:13], v[16:17]
	s_nop 0
	v_pk_fma_f32 v[12:13], v[56:57], v[84:85], v[12:13] op_sel_hi:[0,1,1]
	v_pk_mul_f32 v[8:9], v[8:9], v[12:13]
	v_pk_mul_f32 v[12:13], v[104:105], v[64:65] op_sel_hi:[1,0]
	v_cvt_pk_f16_f32 v8, v8, v9
	v_pk_fma_f32 v[12:13], v[12:13], v[14:15], v[18:19]
	v_pk_mul_f32 v[16:17], v[96:97], v[64:65] op_sel_hi:[1,0]
	v_pk_fma_f32 v[12:13], v[56:57], v[98:99], v[12:13] op_sel_hi:[0,1,1]
	v_pk_mul_f32 v[10:11], v[10:11], v[12:13]
	s_nop 0
	v_cvt_pk_f16_f32 v9, v10, v11
	global_store_dwordx2 v[80:81], v[8:9], off offset:32
	global_load_dwordx4 v[8:11], v[68:69], off offset:128
	s_nop 0
	global_load_dwordx4 v[12:15], v[66:67], off offset:128
	s_waitcnt vmcnt(0)
	v_pk_fma_f32 v[8:9], v[16:17], v[8:9], v[12:13]
	s_nop 0
	v_pk_fma_f32 v[8:9], v[56:57], v[62:63], v[8:9] op_sel_hi:[0,1,1]
	v_pk_mul_f32 v[4:5], v[4:5], v[8:9]
	v_pk_mul_f32 v[8:9], v[58:59], v[64:65] op_sel_hi:[1,0]
	v_cvt_pk_f16_f32 v4, v4, v5
	v_pk_fma_f32 v[8:9], v[8:9], v[10:11], v[14:15]
	v_cvt_f32_f16_e32 v12, v54
	v_pk_fma_f32 v[8:9], v[56:57], v[60:61], v[8:9] op_sel_hi:[0,1,1]
	v_pk_mul_f32 v[6:7], v[6:7], v[8:9]
	v_cvt_f32_f16_sdwa v13, v54 dst_sel:DWORD dst_unused:UNUSED_PAD src0_sel:WORD_1
	v_cvt_pk_f16_f32 v5, v6, v7
	global_store_dwordx2 v[80:81], v[4:5], off offset:64
	global_load_dwordx4 v[4:7], v[68:69], off offset:192
	s_nop 0
	global_load_dwordx4 v[8:11], v[66:67], off offset:192
	v_pk_mul_f32 v[14:15], v[72:73], v[64:65] op_sel_hi:[1,0]
	s_waitcnt vmcnt(0)
	v_pk_fma_f32 v[4:5], v[14:15], v[4:5], v[8:9] op_sel:[1,0,0] op_sel_hi:[0,1,1]
	v_pk_fma_f32 v[4:5], v[56:57], v[12:13], v[4:5] op_sel_hi:[0,1,1]
	v_pk_mul_f32 v[0:1], v[0:1], v[4:5]
	v_cvt_f32_f16_e32 v4, v55
	v_cvt_f32_f16_sdwa v5, v55 dst_sel:DWORD dst_unused:UNUSED_PAD src0_sel:WORD_1
	v_pk_mul_f32 v[8:9], v[70:71], v[64:65] op_sel_hi:[1,0]
	v_cvt_pk_f16_f32 v0, v0, v1
	v_pk_fma_f32 v[6:7], v[8:9], v[6:7], v[10:11] op_sel:[1,0,0] op_sel_hi:[0,1,1]
	v_pk_fma_f32 v[4:5], v[56:57], v[4:5], v[6:7] op_sel_hi:[0,1,1]
	v_pk_mul_f32 v[2:3], v[2:3], v[4:5]
	s_nop 0
	v_cvt_pk_f16_f32 v1, v2, v3
	global_store_dwordx2 v[80:81], v[0:1], off offset:96
	s_cbranch_scc1 .LBB0_1056
